# topk lists: next key tile's sub-key loads issued before the sort/merge network of the current tile (first fragment retargeted to a spare quad), on top of v057
# speedup vs baseline: 1.0124x; 1.0032x over previous
.LBB0_22:
	v_or_b32_e32 v2, s44, v118
	v_mov_b32_e32 v3, v1
	v_lshlrev_b64 v[46:47], 7, v[2:3]
	v_lshl_add_u64 v[2:3], v[62:63], 0, v[46:47]
	global_load_dwordx4 v[30:33], v[2:3], off
	global_load_dwordx4 v[26:29], v[2:3], off offset:32
	global_load_dwordx4 v[22:25], v[2:3], off offset:64
	global_load_dwordx4 v[18:21], v[2:3], off offset:96
	s_nop 0
	global_load_dwordx4 v[2:5], v[66:67], off
	global_load_dwordx4 v[34:37], v[66:67], off offset:32
	global_load_dwordx4 v[38:41], v[66:67], off offset:64
	global_load_dwordx4 v[42:45], v[66:67], off offset:96
	s_waitcnt vmcnt(0)
	v_mfma_f32_32x32x16_bf16 v[2:17], v[2:5], v[30:33], 0
	s_waitcnt vmcnt(2)
	v_mfma_f32_32x32x16_bf16 v[2:17], v[34:37], v[26:29], v[2:17]
	s_waitcnt vmcnt(1)
	v_mfma_f32_32x32x16_bf16 v[2:17], v[38:41], v[22:25], v[2:17]
	s_waitcnt vmcnt(0)
	v_mfma_f32_32x32x16_bf16 v[2:17], v[42:45], v[18:21], v[2:17]
	s_nop 11
	v_and_or_b32 v2, v2, s33, v120
	v_and_or_b32 v3, v3, s33, v122
	v_and_or_b32 v4, v4, s33, v123
	v_and_or_b32 v5, v5, s33, v124
	v_and_or_b32 v6, v6, s33, v125
	v_and_or_b32 v7, v7, s33, v126
	v_and_or_b32 v8, v8, s33, v127
	v_and_or_b32 v9, v9, s33, v128
	v_and_or_b32 v10, v10, s33, v129
	v_and_or_b32 v11, v11, s33, v136
	v_and_or_b32 v12, v12, s33, v137
	v_and_or_b32 v13, v13, s33, v138
	v_and_or_b32 v14, v14, s33, v139
	v_and_or_b32 v15, v15, s33, v140
	v_and_or_b32 v16, v16, s33, v141
	v_and_or_b32 v17, v17, s33, v142
	global_load_dwordx4 v[34:37], v[68:69], off offset:96
	global_load_dwordx4 v[38:41], v[68:69], off offset:64
	global_load_dwordx4 v[42:45], v[68:69], off offset:32
	global_load_dwordx4 v[232:235], v[68:69], off
	v_max_f32_e32 v206, v2, v15
	v_min_f32_e32 v15, v2, v15
	v_max_f32_e32 v207, v3, v14
	v_min_f32_e32 v14, v3, v14
	v_max_f32_e32 v227, v4, v17
	v_min_f32_e32 v17, v4, v17
	v_max_f32_e32 v228, v5, v16
	v_min_f32_e32 v16, v5, v16
	v_max_f32_e32 v229, v6, v10
	v_min_f32_e32 v10, v6, v10
	v_max_f32_e32 v230, v7, v8
	v_min_f32_e32 v8, v7, v8
	v_max_f32_e32 v231, v9, v13
	v_min_f32_e32 v13, v9, v13
	v_max_f32_e32 v2, v11, v12
	v_min_f32_e32 v12, v11, v12
	v_max_f32_e32 v3, v206, v230
	v_min_f32_e32 v230, v206, v230
	v_max_f32_e32 v206, v207, v231
	v_min_f32_e32 v231, v207, v231
	v_max_f32_e32 v207, v227, v2
	v_min_f32_e32 v2, v227, v2
	v_max_f32_e32 v227, v228, v229
	v_min_f32_e32 v229, v228, v229
	v_max_f32_e32 v228, v8, v15
	v_min_f32_e32 v15, v8, v15
	v_max_f32_e32 v4, v10, v16
	v_min_f32_e32 v16, v10, v16
	v_max_f32_e32 v5, v12, v17
	v_min_f32_e32 v17, v12, v17
	v_max_f32_e32 v6, v13, v14
	v_min_f32_e32 v14, v13, v14
	v_max_f32_e32 v7, v3, v206
	v_min_f32_e32 v206, v3, v206
	v_max_f32_e32 v3, v207, v227
	v_min_f32_e32 v227, v207, v227
	v_max_f32_e32 v207, v229, v230
	v_min_f32_e32 v230, v229, v230
	v_max_f32_e32 v229, v228, v4
	v_min_f32_e32 v4, v228, v4
	v_max_f32_e32 v228, v231, v2
	v_min_f32_e32 v2, v231, v2
	v_max_f32_e32 v231, v5, v6
	v_min_f32_e32 v6, v5, v6
	v_max_f32_e32 v5, v14, v15
	v_min_f32_e32 v15, v14, v15
	v_max_f32_e32 v8, v16, v17
	v_min_f32_e32 v17, v16, v17
	v_max_f32_e32 v48, v7, v3
	v_min_f32_e32 v3, v7, v3
	v_max_f32_e32 v7, v206, v227
	v_min_f32_e32 v227, v206, v227
	v_max_f32_e32 v206, v207, v231
	v_min_f32_e32 v231, v207, v231
	v_max_f32_e32 v207, v230, v6
	v_min_f32_e32 v6, v230, v6
	v_max_f32_e32 v230, v229, v228
	v_min_f32_e32 v228, v229, v228
	v_max_f32_e32 v229, v4, v2
	v_min_f32_e32 v2, v4, v2
	v_max_f32_e32 v4, v5, v8
	v_min_f32_e32 v8, v5, v8
	v_min_f32_e32 v205, v15, v17
	v_max_f32_e32 v15, v15, v17
	v_max_f32_e32 v5, v7, v3
	v_min_f32_e32 v3, v7, v3
	v_max_f32_e32 v7, v227, v4
	v_min_f32_e32 v4, v227, v4
	v_max_f32_e32 v227, v206, v230
	v_min_f32_e32 v230, v206, v230
	v_max_f32_e32 v206, v207, v228
	v_min_f32_e32 v228, v207, v228
	v_max_f32_e32 v207, v229, v231
	v_min_f32_e32 v231, v229, v231
	v_max_f32_e32 v229, v2, v6
	v_min_f32_e32 v6, v2, v6
	v_max_f32_e32 v2, v15, v8
	v_min_f32_e32 v8, v15, v8
	v_max_f32_e32 v49, v5, v227
	v_min_f32_e32 v227, v5, v227
	v_max_f32_e32 v5, v3, v230
	v_min_f32_e32 v230, v3, v230
	v_max_f32_e32 v3, v206, v207
	v_min_f32_e32 v207, v206, v207
	v_max_f32_e32 v206, v228, v231
	v_min_f32_e32 v231, v228, v231
	v_max_f32_e32 v228, v229, v2
	v_min_f32_e32 v2, v229, v2
	v_min_f32_e32 v154, v6, v8
	v_max_f32_e32 v6, v6, v8
	v_max_f32_e32 v50, v5, v227
	v_min_f32_e32 v227, v5, v227
	v_max_f32_e32 v229, v7, v230
	v_min_f32_e32 v230, v7, v230
	v_max_f32_e32 v5, v228, v4
	v_min_f32_e32 v4, v228, v4
	v_min_f32_e32 v61, v6, v2
	v_max_f32_e32 v6, v6, v2
	v_max_f32_e32 v228, v229, v3
	v_min_f32_e32 v3, v229, v3
	v_max_f32_e32 v229, v230, v207
	v_min_f32_e32 v207, v230, v207
	v_max_f32_e32 v230, v206, v5
	v_min_f32_e32 v5, v206, v5
	v_max_f32_e32 v206, v231, v4
	v_min_f32_e32 v4, v231, v4
	v_max_f32_e32 v51, v228, v227
	v_min_f32_e32 v52, v228, v227
	v_max_f32_e32 v53, v3, v229
	v_min_f32_e32 v229, v3, v229
	v_max_f32_e32 v227, v230, v207
	v_min_f32_e32 v207, v230, v207
	v_min_f32_e32 v58, v5, v206
	v_max_f32_e32 v5, v5, v206
	v_max_f32_e32 v59, v6, v4
	v_min_f32_e32 v60, v6, v4
	v_max_f32_e32 v54, v229, v227
	v_min_f32_e32 v55, v229, v227
	v_max_f32_e32 v56, v207, v5
	v_min_f32_e32 v57, v207, v5
	s_waitcnt vmcnt(0)
	v_mfma_f32_32x32x16_bf16 v[2:17], v[232:235], v[30:33], 0
	v_mfma_f32_32x32x16_bf16 v[2:17], v[42:45], v[26:29], v[2:17]
	v_mfma_f32_32x32x16_bf16 v[2:17], v[38:41], v[22:25], v[2:17]
	v_mfma_f32_32x32x16_bf16 v[2:17], v[34:37], v[18:21], v[2:17]
	s_nop 11
	v_and_or_b32 v2, v2, s33, v143
	v_and_or_b32 v3, v3, s33, v144
	v_and_or_b32 v4, v4, s33, v145
	v_and_or_b32 v5, v5, s33, v146
	v_and_or_b32 v6, v6, s33, v147
	v_and_or_b32 v7, v7, s33, v148
	v_and_or_b32 v8, v8, s33, v149
	v_and_or_b32 v9, v9, s33, v150
	v_and_or_b32 v10, v10, s33, v151
	v_and_or_b32 v11, v11, s33, v152
	v_and_or_b32 v12, v12, s33, v153
	v_and_or_b32 v13, v13, s33, v160
	v_and_or_b32 v14, v14, s33, v161
	v_and_or_b32 v15, v15, s33, v162
	v_and_or_b32 v16, v16, s33, v163
	v_and_or_b32 v17, v17, s33, v164
	global_load_dwordx4 v[34:37], v[70:71], off offset:96
	global_load_dwordx4 v[38:41], v[70:71], off offset:64
	global_load_dwordx4 v[42:45], v[70:71], off offset:32
	global_load_dwordx4 v[232:235], v[70:71], off
	v_max_f32_e32 v206, v2, v15
	v_min_f32_e32 v15, v2, v15
	v_max_f32_e32 v2, v3, v14
	v_min_f32_e32 v14, v3, v14
	v_max_f32_e32 v3, v4, v17
	v_min_f32_e32 v17, v4, v17
	v_max_f32_e32 v4, v5, v16
	v_min_f32_e32 v16, v5, v16
	v_max_f32_e32 v5, v6, v10
	v_min_f32_e32 v10, v6, v10
	v_max_f32_e32 v6, v7, v8
	v_min_f32_e32 v8, v7, v8
	v_max_f32_e32 v7, v9, v13
	v_min_f32_e32 v13, v9, v13
	v_max_f32_e32 v9, v11, v12
	v_min_f32_e32 v12, v11, v12
	v_max_f32_e32 v11, v206, v6
	v_min_f32_e32 v6, v206, v6
	v_max_f32_e32 v206, v2, v7
	v_min_f32_e32 v7, v2, v7
	v_max_f32_e32 v2, v3, v9
	v_min_f32_e32 v9, v3, v9
	v_max_f32_e32 v3, v4, v5
	v_min_f32_e32 v5, v4, v5
	v_max_f32_e32 v4, v8, v15
	v_min_f32_e32 v15, v8, v15
	v_max_f32_e32 v8, v10, v16
	v_min_f32_e32 v16, v10, v16
	v_max_f32_e32 v10, v12, v17
	v_min_f32_e32 v17, v12, v17
	v_max_f32_e32 v12, v13, v14
	v_min_f32_e32 v14, v13, v14
	v_max_f32_e32 v13, v11, v206
	v_min_f32_e32 v206, v11, v206
	v_max_f32_e32 v11, v2, v3
	v_min_f32_e32 v3, v2, v3
	v_max_f32_e32 v2, v5, v6
	v_min_f32_e32 v6, v5, v6
	v_max_f32_e32 v5, v4, v8
	v_min_f32_e32 v8, v4, v8
	v_max_f32_e32 v4, v7, v9
	v_min_f32_e32 v9, v7, v9
	v_max_f32_e32 v7, v10, v12
	v_min_f32_e32 v12, v10, v12
	v_max_f32_e32 v10, v14, v15
	v_min_f32_e32 v15, v14, v15
	v_max_f32_e32 v14, v16, v17
	v_min_f32_e32 v17, v16, v17
	v_max_f32_e32 v16, v13, v11
	v_min_f32_e32 v11, v13, v11
	v_max_f32_e32 v13, v206, v3
	v_min_f32_e32 v3, v206, v3
	v_max_f32_e32 v206, v2, v7
	v_min_f32_e32 v7, v2, v7
	v_max_f32_e32 v2, v6, v12
	v_min_f32_e32 v12, v6, v12
	v_max_f32_e32 v6, v5, v4
	v_min_f32_e32 v4, v5, v4
	v_max_f32_e32 v5, v8, v9
	v_min_f32_e32 v9, v8, v9
	v_max_f32_e32 v8, v10, v14
	v_min_f32_e32 v14, v10, v14
	v_max_f32_e32 v10, v15, v17
	v_min_f32_e32 v17, v15, v17
	v_max_f32_e32 v15, v13, v11
	v_min_f32_e32 v11, v13, v11
	v_max_f32_e32 v13, v3, v8
	v_min_f32_e32 v8, v3, v8
	v_max_f32_e32 v3, v206, v6
	v_min_f32_e32 v6, v206, v6
	v_max_f32_e32 v206, v2, v4
	v_min_f32_e32 v4, v2, v4
	v_max_f32_e32 v2, v5, v7
	v_min_f32_e32 v7, v5, v7
	v_max_f32_e32 v5, v9, v12
	v_min_f32_e32 v12, v9, v12
	v_max_f32_e32 v9, v10, v14
	v_min_f32_e32 v14, v10, v14
	v_max_f32_e32 v10, v15, v3
	v_min_f32_e32 v3, v15, v3
	v_max_f32_e32 v15, v11, v6
	v_min_f32_e32 v6, v11, v6
	v_max_f32_e32 v11, v206, v2
	v_min_f32_e32 v2, v206, v2
	v_max_f32_e32 v206, v4, v7
	v_min_f32_e32 v7, v4, v7
	v_max_f32_e32 v4, v5, v9
	v_min_f32_e32 v9, v5, v9
	v_max_f32_e32 v5, v12, v14
	v_min_f32_e32 v14, v12, v14
	v_max_f32_e32 v12, v15, v3
	v_min_f32_e32 v3, v15, v3
	v_max_f32_e32 v15, v13, v6
	v_min_f32_e32 v6, v13, v6
	v_max_f32_e32 v13, v4, v8
	v_min_f32_e32 v8, v4, v8
	v_max_f32_e32 v4, v5, v9
	v_min_f32_e32 v9, v5, v9
	v_max_f32_e32 v5, v15, v11
	v_min_f32_e32 v11, v15, v11
	v_max_f32_e32 v15, v6, v2
	v_min_f32_e32 v2, v6, v2
	v_max_f32_e32 v6, v206, v13
	v_min_f32_e32 v13, v206, v13
	v_max_f32_e32 v206, v7, v8
	v_min_f32_e32 v8, v7, v8
	v_max_f32_e32 v7, v5, v3
	v_min_f32_e32 v3, v5, v3
	v_max_f32_e32 v5, v11, v15
	v_min_f32_e32 v15, v11, v15
	v_max_f32_e32 v11, v6, v2
	v_min_f32_e32 v2, v6, v2
	v_max_f32_e32 v6, v13, v206
	v_min_f32_e32 v206, v13, v206
	v_max_f32_e32 v13, v4, v8
	v_min_f32_e32 v8, v4, v8
	v_max_f32_e32 v4, v15, v11
	v_min_f32_e32 v11, v15, v11
	v_max_f32_e32 v15, v2, v6
	v_min_f32_e32 v6, v2, v6
	v_max_f32_e32 v17, v48, v17
	v_max_f32_e32 v14, v49, v14
	v_max_f32_e32 v9, v50, v9
	v_max_f32_e32 v8, v51, v8
	v_max_f32_e32 v13, v52, v13
	v_max_f32_e32 v206, v53, v206
	v_max_f32_e32 v6, v54, v6
	v_max_f32_e32 v15, v55, v15
	v_max_f32_e32 v11, v56, v11
	v_max_f32_e32 v4, v57, v4
	v_max_f32_e32 v5, v58, v5
	v_max_f32_e32 v3, v59, v3
	v_max_f32_e32 v7, v60, v7
	v_max_f32_e32 v12, v61, v12
	v_max_f32_e32 v10, v154, v10
	v_max_f32_e32 v16, v205, v16
	v_max_f32_e32 v2, v16, v15
	v_min_f32_e32 v15, v16, v15
	v_max_f32_e32 v16, v10, v6
	v_min_f32_e32 v6, v10, v6
	v_max_f32_e32 v10, v12, v206
	v_min_f32_e32 v206, v12, v206
	v_max_f32_e32 v12, v7, v13
	v_min_f32_e32 v13, v7, v13
	v_max_f32_e32 v7, v3, v8
	v_min_f32_e32 v8, v3, v8
	v_max_f32_e32 v3, v5, v9
	v_min_f32_e32 v9, v5, v9
	v_max_f32_e32 v5, v4, v14
	v_min_f32_e32 v14, v4, v14
	v_max_f32_e32 v4, v11, v17
	v_min_f32_e32 v17, v11, v17
	v_max_f32_e32 v11, v2, v7
	v_min_f32_e32 v7, v2, v7
	v_max_f32_e32 v2, v16, v3
	v_min_f32_e32 v3, v16, v3
	v_max_f32_e32 v16, v10, v5
	v_min_f32_e32 v5, v10, v5
	v_max_f32_e32 v10, v12, v4
	v_min_f32_e32 v4, v12, v4
	v_max_f32_e32 v12, v15, v8
	v_min_f32_e32 v8, v15, v8
	v_max_f32_e32 v15, v6, v9
	v_min_f32_e32 v9, v6, v9
	v_max_f32_e32 v6, v206, v14
	v_min_f32_e32 v14, v206, v14
	v_max_f32_e32 v48, v13, v17
	v_min_f32_e32 v17, v13, v17
	v_max_f32_e32 v13, v11, v16
	v_min_f32_e32 v16, v11, v16
	v_max_f32_e32 v11, v2, v10
	v_min_f32_e32 v10, v2, v10
	v_max_f32_e32 v2, v7, v5
	v_min_f32_e32 v5, v7, v5
	v_max_f32_e32 v7, v3, v4
	v_min_f32_e32 v4, v3, v4
	v_max_f32_e32 v3, v12, v6
	v_min_f32_e32 v6, v12, v6
	v_max_f32_e32 v12, v15, v48
	v_min_f32_e32 v48, v15, v48
	v_max_f32_e32 v15, v8, v14
	v_min_f32_e32 v14, v8, v14
	v_max_f32_e32 v8, v9, v17
	v_min_f32_e32 v17, v9, v17
	v_max_f32_e32 v206, v13, v11
	v_min_f32_e32 v207, v13, v11
	v_max_f32_e32 v227, v16, v10
	v_min_f32_e32 v228, v16, v10
	v_max_f32_e32 v229, v2, v7
	v_min_f32_e32 v230, v2, v7
	v_max_f32_e32 v231, v5, v4
	v_min_f32_e32 v4, v5, v4
	v_max_f32_e32 v49, v3, v12
	v_min_f32_e32 v50, v3, v12
	v_max_f32_e32 v51, v6, v48
	v_min_f32_e32 v52, v6, v48
	v_max_f32_e32 v53, v15, v8
	v_min_f32_e32 v54, v15, v8
	v_max_f32_e32 v55, v14, v17
	v_min_f32_e32 v56, v14, v17
	v_mov_b32_e32 v48, v4
	s_waitcnt vmcnt(0)
	v_mfma_f32_32x32x16_bf16 v[2:17], v[232:235], v[30:33], 0
	v_mfma_f32_32x32x16_bf16 v[2:17], v[42:45], v[26:29], v[2:17]
	v_mfma_f32_32x32x16_bf16 v[2:17], v[38:41], v[22:25], v[2:17]
	v_mfma_f32_32x32x16_bf16 v[2:17], v[34:37], v[18:21], v[2:17]
	s_nop 11
	v_and_or_b32 v2, v2, s33, v165
	v_and_or_b32 v3, v3, s33, v166
	v_and_or_b32 v4, v4, s33, v167
	v_and_or_b32 v5, v5, s33, v168
	v_and_or_b32 v6, v6, s33, v169
	v_and_or_b32 v7, v7, s33, v170
	v_and_or_b32 v8, v8, s33, v171
	v_and_or_b32 v9, v9, s33, v172
	v_and_or_b32 v10, v10, s33, v173
	v_and_or_b32 v11, v11, s33, v174
	v_and_or_b32 v12, v12, s33, v175
	v_and_or_b32 v13, v13, s33, v184
	v_and_or_b32 v14, v14, s33, v185
	v_and_or_b32 v15, v15, s33, v186
	v_and_or_b32 v16, v16, s33, v187
	v_and_or_b32 v17, v17, s33, v188
	global_load_dwordx4 v[34:37], v[72:73], off offset:96
	global_load_dwordx4 v[38:41], v[72:73], off offset:64
	global_load_dwordx4 v[42:45], v[72:73], off offset:32
	global_load_dwordx4 v[232:235], v[72:73], off
	v_max_f32_e32 v57, v2, v15
	v_min_f32_e32 v15, v2, v15
	v_max_f32_e32 v2, v3, v14
	v_min_f32_e32 v14, v3, v14
	v_max_f32_e32 v3, v4, v17
	v_min_f32_e32 v17, v4, v17
	v_max_f32_e32 v4, v5, v16
	v_min_f32_e32 v16, v5, v16
	v_max_f32_e32 v5, v6, v10
	v_min_f32_e32 v10, v6, v10
	v_max_f32_e32 v6, v7, v8
	v_min_f32_e32 v8, v7, v8
	v_max_f32_e32 v7, v9, v13
	v_min_f32_e32 v13, v9, v13
	v_max_f32_e32 v9, v11, v12
	v_min_f32_e32 v12, v11, v12
	v_max_f32_e32 v11, v57, v6
	v_min_f32_e32 v6, v57, v6
	v_max_f32_e32 v57, v2, v7
	v_min_f32_e32 v7, v2, v7
	v_max_f32_e32 v2, v3, v9
	v_min_f32_e32 v9, v3, v9
	v_max_f32_e32 v3, v4, v5
	v_min_f32_e32 v5, v4, v5
	v_max_f32_e32 v4, v8, v15
	v_min_f32_e32 v15, v8, v15
	v_max_f32_e32 v8, v10, v16
	v_min_f32_e32 v16, v10, v16
	v_max_f32_e32 v10, v12, v17
	v_min_f32_e32 v17, v12, v17
	v_max_f32_e32 v12, v13, v14
	v_min_f32_e32 v14, v13, v14
	v_max_f32_e32 v13, v11, v57
	v_min_f32_e32 v57, v11, v57
	v_max_f32_e32 v11, v2, v3
	v_min_f32_e32 v3, v2, v3
	v_max_f32_e32 v2, v5, v6
	v_min_f32_e32 v6, v5, v6
	v_max_f32_e32 v5, v4, v8
	v_min_f32_e32 v8, v4, v8
	v_max_f32_e32 v4, v7, v9
	v_min_f32_e32 v9, v7, v9
	v_max_f32_e32 v7, v10, v12
	v_min_f32_e32 v12, v10, v12
	v_max_f32_e32 v10, v14, v15
	v_min_f32_e32 v15, v14, v15
	v_max_f32_e32 v14, v16, v17
	v_min_f32_e32 v17, v16, v17
	v_max_f32_e32 v16, v13, v11
	v_min_f32_e32 v11, v13, v11
	v_max_f32_e32 v13, v57, v3
	v_min_f32_e32 v3, v57, v3
	v_max_f32_e32 v57, v2, v7
	v_min_f32_e32 v7, v2, v7
	v_max_f32_e32 v2, v6, v12
	v_min_f32_e32 v12, v6, v12
	v_max_f32_e32 v6, v5, v4
	v_min_f32_e32 v4, v5, v4
	v_max_f32_e32 v5, v8, v9
	v_min_f32_e32 v9, v8, v9
	v_max_f32_e32 v8, v10, v14
	v_min_f32_e32 v14, v10, v14
	v_max_f32_e32 v10, v15, v17
	v_min_f32_e32 v17, v15, v17
	v_max_f32_e32 v15, v13, v11
	v_min_f32_e32 v11, v13, v11
	v_max_f32_e32 v13, v3, v8
	v_min_f32_e32 v8, v3, v8
	v_max_f32_e32 v3, v57, v6
	v_min_f32_e32 v6, v57, v6
	v_max_f32_e32 v57, v2, v4
	v_min_f32_e32 v4, v2, v4
	v_max_f32_e32 v2, v5, v7
	v_min_f32_e32 v7, v5, v7
	v_max_f32_e32 v5, v9, v12
	v_min_f32_e32 v12, v9, v12
	v_max_f32_e32 v9, v10, v14
	v_min_f32_e32 v14, v10, v14
	v_max_f32_e32 v10, v15, v3
	v_min_f32_e32 v3, v15, v3
	v_max_f32_e32 v15, v11, v6
	v_min_f32_e32 v6, v11, v6
	v_max_f32_e32 v11, v57, v2
	v_min_f32_e32 v2, v57, v2
	v_max_f32_e32 v57, v4, v7
	v_min_f32_e32 v7, v4, v7
	v_max_f32_e32 v4, v5, v9
	v_min_f32_e32 v9, v5, v9
	v_max_f32_e32 v5, v12, v14
	v_min_f32_e32 v14, v12, v14
	v_max_f32_e32 v12, v15, v3
	v_min_f32_e32 v3, v15, v3
	v_max_f32_e32 v15, v13, v6
	v_min_f32_e32 v6, v13, v6
	v_max_f32_e32 v13, v4, v8
	v_min_f32_e32 v8, v4, v8
	v_max_f32_e32 v4, v5, v9
	v_min_f32_e32 v9, v5, v9
	v_max_f32_e32 v5, v15, v11
	v_min_f32_e32 v11, v15, v11
	v_max_f32_e32 v15, v6, v2
	v_min_f32_e32 v2, v6, v2
	v_max_f32_e32 v6, v57, v13
	v_min_f32_e32 v13, v57, v13
	v_max_f32_e32 v57, v7, v8
	v_min_f32_e32 v8, v7, v8
	v_max_f32_e32 v7, v5, v3
	v_min_f32_e32 v3, v5, v3
	v_max_f32_e32 v5, v11, v15
	v_min_f32_e32 v15, v11, v15
	v_max_f32_e32 v11, v6, v2
	v_min_f32_e32 v2, v6, v2
	v_max_f32_e32 v6, v13, v57
	v_min_f32_e32 v57, v13, v57
	v_max_f32_e32 v13, v4, v8
	v_min_f32_e32 v8, v4, v8
	v_max_f32_e32 v4, v15, v11
	v_min_f32_e32 v11, v15, v11
	v_max_f32_e32 v15, v2, v6
	v_min_f32_e32 v6, v2, v6
	v_max_f32_e32 v17, v206, v17
	v_max_f32_e32 v14, v207, v14
	v_max_f32_e32 v9, v227, v9
	v_max_f32_e32 v8, v228, v8
	v_max_f32_e32 v13, v229, v13
	v_max_f32_e32 v57, v230, v57
	v_max_f32_e32 v6, v231, v6
	v_max_f32_e32 v15, v48, v15
	v_max_f32_e32 v11, v49, v11
	v_max_f32_e32 v4, v50, v4
	v_max_f32_e32 v5, v51, v5
	v_max_f32_e32 v3, v52, v3
	v_max_f32_e32 v7, v53, v7
	v_max_f32_e32 v12, v54, v12
	v_max_f32_e32 v10, v55, v10
	v_max_f32_e32 v16, v56, v16
	v_max_f32_e32 v2, v16, v15
	v_min_f32_e32 v15, v16, v15
	v_max_f32_e32 v16, v10, v6
	v_min_f32_e32 v6, v10, v6
	v_max_f32_e32 v10, v12, v57
	v_min_f32_e32 v57, v12, v57
	v_max_f32_e32 v12, v7, v13
	v_min_f32_e32 v13, v7, v13
	v_max_f32_e32 v7, v3, v8
	v_min_f32_e32 v8, v3, v8
	v_max_f32_e32 v3, v5, v9
	v_min_f32_e32 v9, v5, v9
	v_max_f32_e32 v5, v4, v14
	v_min_f32_e32 v14, v4, v14
	v_max_f32_e32 v4, v11, v17
	v_min_f32_e32 v17, v11, v17
	v_max_f32_e32 v11, v2, v7
	v_min_f32_e32 v7, v2, v7
	v_max_f32_e32 v2, v16, v3
	v_min_f32_e32 v3, v16, v3
	v_max_f32_e32 v16, v10, v5
	v_min_f32_e32 v5, v10, v5
	v_max_f32_e32 v10, v12, v4
	v_min_f32_e32 v4, v12, v4
	v_max_f32_e32 v12, v15, v8
	v_min_f32_e32 v8, v15, v8
	v_max_f32_e32 v15, v6, v9
	v_min_f32_e32 v9, v6, v9
	v_max_f32_e32 v6, v57, v14
	v_min_f32_e32 v14, v57, v14
	v_max_f32_e32 v206, v13, v17
	v_min_f32_e32 v17, v13, v17
	v_max_f32_e32 v13, v11, v16
	v_min_f32_e32 v16, v11, v16
	v_max_f32_e32 v11, v2, v10
	v_min_f32_e32 v10, v2, v10
	v_max_f32_e32 v2, v7, v5
	v_min_f32_e32 v5, v7, v5
	v_max_f32_e32 v7, v3, v4
	v_min_f32_e32 v4, v3, v4
	v_max_f32_e32 v3, v12, v6
	v_min_f32_e32 v6, v12, v6
	v_max_f32_e32 v12, v15, v206
	v_min_f32_e32 v206, v15, v206
	v_max_f32_e32 v15, v8, v14
	v_min_f32_e32 v14, v8, v14
	v_max_f32_e32 v8, v9, v17
	v_min_f32_e32 v17, v9, v17
	v_max_f32_e32 v57, v13, v11
	v_min_f32_e32 v58, v13, v11
	v_max_f32_e32 v59, v16, v10
	v_min_f32_e32 v60, v16, v10
	v_max_f32_e32 v61, v2, v7
	v_min_f32_e32 v154, v2, v7
	v_max_f32_e32 v205, v5, v4
	v_min_f32_e32 v48, v5, v4
	v_max_f32_e32 v49, v3, v12
	v_min_f32_e32 v50, v3, v12
	v_max_f32_e32 v51, v6, v206
	v_min_f32_e32 v52, v6, v206
	v_max_f32_e32 v53, v15, v8
	v_min_f32_e32 v54, v15, v8
	v_max_f32_e32 v55, v14, v17
	v_min_f32_e32 v56, v14, v17
	s_waitcnt vmcnt(0)
	v_mfma_f32_32x32x16_bf16 v[2:17], v[232:235], v[30:33], 0
	v_mfma_f32_32x32x16_bf16 v[2:17], v[42:45], v[26:29], v[2:17]
	v_mfma_f32_32x32x16_bf16 v[2:17], v[38:41], v[22:25], v[2:17]
	v_mfma_f32_32x32x16_bf16 v[2:17], v[34:37], v[18:21], v[2:17]
	s_nop 11
	v_and_or_b32 v2, v2, s33, v189
	v_and_or_b32 v3, v3, s33, v190
	v_and_or_b32 v4, v4, s33, v191
	v_and_or_b32 v5, v5, s33, v192
	v_and_or_b32 v6, v6, s33, v193
	v_and_or_b32 v7, v7, s33, v194
	v_and_or_b32 v8, v8, s33, v195
	v_and_or_b32 v9, v9, s33, v196
	v_and_or_b32 v10, v10, s33, v197
	v_and_or_b32 v11, v11, s33, v198
	v_and_or_b32 v12, v12, s33, v199
	v_and_or_b32 v13, v13, s33, v200
	v_and_or_b32 v14, v14, s33, v201
	v_and_or_b32 v15, v15, s33, v202
	v_and_or_b32 v16, v16, s33, v203
	v_and_or_b32 v17, v17, s33, v204
	v_max_f32_e32 v19, v2, v15
	v_min_f32_e32 v15, v2, v15
	v_max_f32_e32 v20, v3, v14
	v_min_f32_e32 v14, v3, v14
	v_max_f32_e32 v21, v4, v17
	v_min_f32_e32 v17, v4, v17
	v_max_f32_e32 v22, v5, v16
	v_min_f32_e32 v16, v5, v16
	v_max_f32_e32 v23, v6, v10
	v_min_f32_e32 v10, v6, v10
	v_max_f32_e32 v24, v7, v8
	v_min_f32_e32 v8, v7, v8
	v_max_f32_e32 v25, v9, v13
	v_min_f32_e32 v13, v9, v13
	v_max_f32_e32 v26, v11, v12
	v_min_f32_e32 v12, v11, v12
	v_max_f32_e32 v27, v19, v24
	v_min_f32_e32 v24, v19, v24
	v_max_f32_e32 v19, v20, v25
	v_min_f32_e32 v25, v20, v25
	v_max_f32_e32 v20, v21, v26
	v_min_f32_e32 v26, v21, v26
	v_max_f32_e32 v21, v22, v23
	v_min_f32_e32 v23, v22, v23
	v_max_f32_e32 v22, v8, v15
	v_min_f32_e32 v15, v8, v15
	v_max_f32_e32 v28, v10, v16
	v_min_f32_e32 v16, v10, v16
	v_max_f32_e32 v29, v12, v17
	v_min_f32_e32 v17, v12, v17
	v_max_f32_e32 v30, v13, v14
	v_min_f32_e32 v14, v13, v14
	v_max_f32_e32 v31, v27, v19
	v_min_f32_e32 v19, v27, v19
	v_max_f32_e32 v27, v20, v21
	v_min_f32_e32 v21, v20, v21
	v_max_f32_e32 v20, v23, v24
	v_min_f32_e32 v24, v23, v24
	v_max_f32_e32 v23, v22, v28
	v_min_f32_e32 v28, v22, v28
	v_max_f32_e32 v22, v25, v26
	v_min_f32_e32 v26, v25, v26
	v_max_f32_e32 v25, v29, v30
	v_min_f32_e32 v30, v29, v30
	v_max_f32_e32 v29, v14, v15
	v_min_f32_e32 v15, v14, v15
	v_max_f32_e32 v32, v16, v17
	v_min_f32_e32 v17, v16, v17
	v_max_f32_e32 v2, v31, v27
	v_min_f32_e32 v27, v31, v27
	v_max_f32_e32 v31, v19, v21
	v_min_f32_e32 v21, v19, v21
	v_max_f32_e32 v19, v20, v25
	v_min_f32_e32 v25, v20, v25
	v_max_f32_e32 v20, v24, v30
	v_min_f32_e32 v30, v24, v30
	v_max_f32_e32 v24, v23, v22
	v_min_f32_e32 v22, v23, v22
	v_max_f32_e32 v23, v28, v26
	v_min_f32_e32 v26, v28, v26
	v_max_f32_e32 v28, v29, v32
	v_min_f32_e32 v32, v29, v32
	v_max_f32_e32 v29, v15, v17
	v_min_f32_e32 v17, v15, v17
	v_max_f32_e32 v3, v31, v27
	v_min_f32_e32 v27, v31, v27
	v_max_f32_e32 v31, v21, v28
	v_min_f32_e32 v28, v21, v28
	v_max_f32_e32 v21, v19, v24
	v_min_f32_e32 v24, v19, v24
	v_max_f32_e32 v19, v20, v22
	v_min_f32_e32 v22, v20, v22
	v_max_f32_e32 v20, v23, v25
	v_min_f32_e32 v25, v23, v25
	v_max_f32_e32 v23, v26, v30
	v_min_f32_e32 v30, v26, v30
	v_max_f32_e32 v26, v29, v32
	v_min_f32_e32 v32, v29, v32
	v_max_f32_e32 v29, v3, v21
	v_min_f32_e32 v21, v3, v21
	v_max_f32_e32 v3, v27, v24
	v_min_f32_e32 v24, v27, v24
	v_max_f32_e32 v27, v19, v20
	v_min_f32_e32 v20, v19, v20
	v_max_f32_e32 v19, v22, v25
	v_min_f32_e32 v25, v22, v25
	v_max_f32_e32 v22, v23, v26
	v_min_f32_e32 v26, v23, v26
	v_max_f32_e32 v23, v30, v32
	v_min_f32_e32 v32, v30, v32
	v_max_f32_e32 v30, v3, v21
	v_min_f32_e32 v21, v3, v21
	v_max_f32_e32 v3, v31, v24
	v_min_f32_e32 v24, v31, v24
	v_max_f32_e32 v31, v22, v28
	v_min_f32_e32 v28, v22, v28
	v_max_f32_e32 v22, v23, v26
	v_min_f32_e32 v26, v23, v26
	v_max_f32_e32 v23, v3, v27
	v_min_f32_e32 v27, v3, v27
	v_max_f32_e32 v3, v24, v20
	v_min_f32_e32 v20, v24, v20
	v_max_f32_e32 v24, v19, v31
	v_min_f32_e32 v31, v19, v31
	v_max_f32_e32 v19, v25, v28
	v_min_f32_e32 v28, v25, v28
	v_max_f32_e32 v25, v23, v21
	v_min_f32_e32 v21, v23, v21
	v_max_f32_e32 v23, v27, v3
	v_min_f32_e32 v3, v27, v3
	v_max_f32_e32 v27, v24, v20
	v_min_f32_e32 v20, v24, v20
	v_max_f32_e32 v24, v31, v19
	v_min_f32_e32 v19, v31, v19
	v_max_f32_e32 v31, v22, v28
	v_min_f32_e32 v28, v22, v28
	v_max_f32_e32 v22, v3, v27
	v_min_f32_e32 v27, v3, v27
	v_max_f32_e32 v3, v20, v24
	v_min_f32_e32 v24, v20, v24
	v_max_f32_e32 v17, v57, v17
	v_max_f32_e32 v32, v58, v32
	v_max_f32_e32 v26, v59, v26
	v_max_f32_e32 v28, v60, v28
	v_max_f32_e32 v31, v61, v31
	v_max_f32_e32 v19, v154, v19
	v_max_f32_e32 v24, v205, v24
	v_max_f32_e32 v3, v48, v3
	v_max_f32_e32 v27, v49, v27
	v_max_f32_e32 v22, v50, v22
	v_max_f32_e32 v23, v51, v23
	v_max_f32_e32 v21, v52, v21
	v_max_f32_e32 v25, v53, v25
	v_max_f32_e32 v30, v54, v30
	v_max_f32_e32 v29, v55, v29
	v_max_f32_e32 v2, v56, v2
	v_max_f32_e32 v20, v2, v3
	v_min_f32_e32 v3, v2, v3
	v_max_f32_e32 v2, v29, v24
	v_min_f32_e32 v24, v29, v24
	v_max_f32_e32 v29, v30, v19
	v_min_f32_e32 v19, v30, v19
	v_max_f32_e32 v30, v25, v31
	v_min_f32_e32 v31, v25, v31
	v_max_f32_e32 v25, v21, v28
	v_min_f32_e32 v28, v21, v28
	v_max_f32_e32 v21, v23, v26
	v_min_f32_e32 v26, v23, v26
	v_max_f32_e32 v23, v22, v32
	v_min_f32_e32 v32, v22, v32
	v_max_f32_e32 v22, v27, v17
	v_min_f32_e32 v17, v27, v17
	v_max_f32_e32 v27, v20, v25
	v_min_f32_e32 v25, v20, v25
	v_max_f32_e32 v20, v2, v21
	v_min_f32_e32 v21, v2, v21
	v_max_f32_e32 v2, v29, v23
	v_min_f32_e32 v23, v29, v23
	v_max_f32_e32 v29, v30, v22
	v_min_f32_e32 v22, v30, v22
	v_max_f32_e32 v30, v3, v28
	v_min_f32_e32 v28, v3, v28
	v_max_f32_e32 v3, v24, v26
	v_min_f32_e32 v26, v24, v26
	v_max_f32_e32 v24, v19, v32
	v_min_f32_e32 v32, v19, v32
	v_max_f32_e32 v19, v31, v17
	v_min_f32_e32 v17, v31, v17
	v_max_f32_e32 v31, v27, v2
	v_min_f32_e32 v2, v27, v2
	v_max_f32_e32 v27, v20, v29
	v_min_f32_e32 v29, v20, v29
	v_max_f32_e32 v20, v25, v23
	v_min_f32_e32 v23, v25, v23
	v_max_f32_e32 v25, v21, v22
	v_min_f32_e32 v22, v21, v22
	v_max_f32_e32 v21, v30, v24
	v_min_f32_e32 v24, v30, v24
	v_max_f32_e32 v30, v3, v19
	v_min_f32_e32 v19, v3, v19
	v_max_f32_e32 v3, v28, v32
	v_min_f32_e32 v32, v28, v32
	v_max_f32_e32 v28, v26, v17
	v_min_f32_e32 v17, v26, v17
	v_max_f32_e32 v15, v31, v27
	v_min_f32_e32 v27, v31, v27
	v_max_f32_e32 v12, v2, v29
	v_min_f32_e32 v5, v2, v29
	v_max_f32_e32 v9, v20, v25
	v_min_f32_e32 v25, v20, v25
	v_max_f32_e32 v18, v23, v22
	v_min_f32_e32 v4, v23, v22
	v_max_f32_e32 v11, v21, v30
	v_min_f32_e32 v13, v21, v30
	v_max_f32_e32 v16, v24, v19
	v_min_f32_e32 v7, v24, v19
	v_max_f32_e32 v14, v3, v28
	v_min_f32_e32 v8, v3, v28
	v_max_f32_e32 v10, v32, v17
	v_min_f32_e32 v2, v32, v17
	v_mov_b32_e32 v3, v27
	v_mov_b32_e32 v17, v25
	ds_bpermute_b32 v6, v121, v15
	ds_bpermute_b32 v19, v121, v3
	ds_bpermute_b32 v20, v121, v12
	ds_bpermute_b32 v21, v121, v5
	ds_bpermute_b32 v22, v121, v9
	ds_bpermute_b32 v23, v121, v17
	ds_bpermute_b32 v24, v121, v18
	ds_bpermute_b32 v25, v121, v4
	ds_bpermute_b32 v26, v121, v11
	ds_bpermute_b32 v27, v121, v13
	ds_bpermute_b32 v28, v121, v16
	ds_bpermute_b32 v29, v121, v7
	ds_bpermute_b32 v30, v121, v14
	ds_bpermute_b32 v31, v121, v8
	ds_bpermute_b32 v32, v121, v10
	ds_bpermute_b32 v33, v121, v2
	s_waitcnt lgkmcnt(4)
	s_waitcnt lgkmcnt(3)
	s_waitcnt lgkmcnt(2)
	s_waitcnt lgkmcnt(1)
	s_waitcnt lgkmcnt(0)
	v_max_f32_e32 v15, v15, v33
	v_max_f32_e32 v3, v3, v32
	v_max_f32_e32 v12, v12, v31
	v_max_f32_e32 v5, v5, v30
	v_max_f32_e32 v9, v9, v29
	v_max_f32_e32 v17, v17, v28
	v_max_f32_e32 v18, v18, v27
	v_max_f32_e32 v4, v4, v26
	v_max_f32_e32 v11, v11, v25
	v_max_f32_e32 v13, v13, v24
	v_max_f32_e32 v16, v16, v23
	v_max_f32_e32 v7, v7, v22
	v_max_f32_e32 v14, v14, v21
	v_max_f32_e32 v8, v8, v20
	v_max_f32_e32 v10, v10, v19
	v_max_f32_e32 v2, v2, v6
	v_max_f32_e32 v6, v15, v11
	v_min_f32_e32 v11, v15, v11
	v_max_f32_e32 v15, v3, v13
	v_min_f32_e32 v3, v3, v13
	v_max_f32_e32 v13, v12, v16
	v_min_f32_e32 v12, v12, v16
	v_max_f32_e32 v16, v5, v7
	v_min_f32_e32 v5, v5, v7
	v_max_f32_e32 v7, v9, v14
	v_min_f32_e32 v9, v9, v14
	v_max_f32_e32 v14, v17, v8
	v_min_f32_e32 v8, v17, v8
	v_max_f32_e32 v17, v18, v10
	v_min_f32_e32 v10, v18, v10
	v_max_f32_e32 v18, v4, v2
	v_min_f32_e32 v2, v4, v2
	v_max_f32_e32 v4, v6, v7
	v_min_f32_e32 v6, v6, v7
	v_max_f32_e32 v7, v15, v14
	v_min_f32_e32 v14, v15, v14
	v_max_f32_e32 v15, v13, v17
	v_min_f32_e32 v13, v13, v17
	v_max_f32_e32 v17, v16, v18
	v_min_f32_e32 v16, v16, v18
	v_max_f32_e32 v18, v11, v9
	v_min_f32_e32 v9, v11, v9
	v_max_f32_e32 v11, v3, v8
	v_min_f32_e32 v3, v3, v8
	v_max_f32_e32 v8, v12, v10
	v_min_f32_e32 v10, v12, v10
	v_max_f32_e32 v12, v5, v2
	v_min_f32_e32 v2, v5, v2
	v_max_f32_e32 v5, v4, v15
	v_min_f32_e32 v4, v4, v15
	v_max_f32_e32 v15, v7, v17
	v_min_f32_e32 v7, v7, v17
	v_max_f32_e32 v17, v6, v13
	v_min_f32_e32 v6, v6, v13
	v_max_f32_e32 v13, v14, v16
	v_min_f32_e32 v14, v14, v16
	v_max_f32_e32 v16, v18, v8
	v_min_f32_e32 v8, v18, v8
	v_max_f32_e32 v18, v11, v12
	v_min_f32_e32 v11, v11, v12
	v_max_f32_e32 v12, v9, v10
	v_min_f32_e32 v9, v9, v10
	v_max_f32_e32 v10, v3, v2
	v_min_f32_e32 v2, v3, v2
	v_max_f32_e32 v20, v9, v2
	v_min_f32_e32 v21, v9, v2
	v_lshl_add_u64 v[2:3], v[64:65], 0, v[46:47]
	v_max_f32_e32 v30, v5, v15
	v_min_f32_e32 v31, v5, v15
	v_max_f32_e32 v32, v4, v7
	v_min_f32_e32 v33, v4, v7
	global_load_dwordx4 v[46:49], v[2:3], off
	global_load_dwordx4 v[42:45], v[2:3], off offset:32
	global_load_dwordx4 v[38:41], v[2:3], off offset:64
	global_load_dwordx4 v[34:37], v[2:3], off offset:96
	s_nop 0
	global_load_dwordx4 v[2:5], v[90:91], off
	global_load_dwordx4 v[58:61], v[90:91], off offset:32
	global_load_dwordx4 v[54:57], v[90:91], off offset:64
	global_load_dwordx4 v[50:53], v[90:91], off offset:96
	v_max_f32_e32 v26, v17, v13
	v_min_f32_e32 v27, v17, v13
	v_max_f32_e32 v28, v6, v14
	v_min_f32_e32 v29, v6, v14
	v_max_f32_e32 v22, v16, v18
	v_min_f32_e32 v23, v16, v18
	v_max_f32_e32 v24, v8, v11
	v_min_f32_e32 v25, v8, v11
	v_max_f32_e32 v18, v12, v10
	v_min_f32_e32 v19, v12, v10
	s_waitcnt vmcnt(3)
	v_mfma_f32_32x32x16_bf16 v[2:17], v[2:5], v[46:49], 0
	s_waitcnt vmcnt(2)
	v_mfma_f32_32x32x16_bf16 v[2:17], v[58:61], v[42:45], v[2:17]
	s_waitcnt vmcnt(1)
	v_mfma_f32_32x32x16_bf16 v[2:17], v[54:57], v[38:41], v[2:17]
	s_waitcnt vmcnt(0)
	v_mfma_f32_32x32x16_bf16 v[2:17], v[50:53], v[34:37], v[2:17]
	s_nop 11
	v_and_or_b32 v2, v2, s33, v120
	v_and_or_b32 v3, v3, s33, v122
	v_and_or_b32 v4, v4, s33, v123
	v_and_or_b32 v5, v5, s33, v124
	v_and_or_b32 v6, v6, s33, v125
	v_and_or_b32 v7, v7, s33, v126
	v_and_or_b32 v8, v8, s33, v127
	v_and_or_b32 v9, v9, s33, v128
	v_and_or_b32 v10, v10, s33, v129
	v_and_or_b32 v11, v11, s33, v136
	v_and_or_b32 v12, v12, s33, v137
	v_and_or_b32 v13, v13, s33, v138
	v_and_or_b32 v14, v14, s33, v139
	v_and_or_b32 v15, v15, s33, v140
	v_and_or_b32 v16, v16, s33, v141
	v_and_or_b32 v17, v17, s33, v142
	global_load_dwordx4 v[50:53], v[92:93], off offset:96
	global_load_dwordx4 v[54:57], v[92:93], off offset:64
	global_load_dwordx4 v[58:61], v[92:93], off offset:32
	global_load_dwordx4 v[244:247], v[92:93], off
	v_max_f32_e32 v239, v2, v15
	v_min_f32_e32 v15, v2, v15
	v_max_f32_e32 v240, v3, v14
	v_min_f32_e32 v14, v3, v14
	v_max_f32_e32 v241, v4, v17
	v_min_f32_e32 v17, v4, v17
	v_max_f32_e32 v242, v5, v16
	v_min_f32_e32 v16, v5, v16
	v_max_f32_e32 v243, v6, v10
	v_min_f32_e32 v10, v6, v10
	v_max_f32_e32 v2, v7, v8
	v_min_f32_e32 v8, v7, v8
	v_max_f32_e32 v3, v9, v13
	v_min_f32_e32 v13, v9, v13
	v_max_f32_e32 v4, v11, v12
	v_min_f32_e32 v12, v11, v12
	v_max_f32_e32 v5, v239, v2
	v_min_f32_e32 v2, v239, v2
	v_max_f32_e32 v239, v240, v3
	v_min_f32_e32 v3, v240, v3
	v_max_f32_e32 v240, v241, v4
	v_min_f32_e32 v4, v241, v4
	v_max_f32_e32 v241, v242, v243
	v_min_f32_e32 v243, v242, v243
	v_max_f32_e32 v242, v8, v15
	v_min_f32_e32 v15, v8, v15
	v_max_f32_e32 v6, v10, v16
	v_min_f32_e32 v16, v10, v16
	v_max_f32_e32 v7, v12, v17
	v_min_f32_e32 v17, v12, v17
	v_max_f32_e32 v8, v13, v14
	v_min_f32_e32 v14, v13, v14
	v_max_f32_e32 v9, v5, v239
	v_min_f32_e32 v239, v5, v239
	v_max_f32_e32 v5, v240, v241
	v_min_f32_e32 v241, v240, v241
	v_max_f32_e32 v240, v243, v2
	v_min_f32_e32 v2, v243, v2
	v_max_f32_e32 v243, v242, v6
	v_min_f32_e32 v6, v242, v6
	v_max_f32_e32 v242, v3, v4
	v_min_f32_e32 v4, v3, v4
	v_max_f32_e32 v3, v7, v8
	v_min_f32_e32 v8, v7, v8
	v_max_f32_e32 v7, v14, v15
	v_min_f32_e32 v15, v14, v15
	v_max_f32_e32 v10, v16, v17
	v_min_f32_e32 v17, v16, v17
	v_max_f32_e32 v154, v9, v5
	v_min_f32_e32 v5, v9, v5
	v_max_f32_e32 v9, v239, v241
	v_min_f32_e32 v241, v239, v241
	v_max_f32_e32 v239, v240, v3
	v_min_f32_e32 v3, v240, v3
	v_max_f32_e32 v240, v2, v8
	v_min_f32_e32 v8, v2, v8
	v_max_f32_e32 v2, v243, v242
	v_min_f32_e32 v242, v243, v242
	v_max_f32_e32 v243, v6, v4
	v_min_f32_e32 v4, v6, v4
	v_max_f32_e32 v6, v7, v10
	v_min_f32_e32 v10, v7, v10
	v_min_f32_e32 v238, v15, v17
	v_max_f32_e32 v15, v15, v17
	v_max_f32_e32 v7, v9, v5
	v_min_f32_e32 v5, v9, v5
	v_max_f32_e32 v9, v241, v6
	v_min_f32_e32 v6, v241, v6
	v_max_f32_e32 v241, v239, v2
	v_min_f32_e32 v2, v239, v2
	v_max_f32_e32 v239, v240, v242
	v_min_f32_e32 v242, v240, v242
	v_max_f32_e32 v240, v243, v3
	v_min_f32_e32 v3, v243, v3
	v_max_f32_e32 v243, v4, v8
	v_min_f32_e32 v8, v4, v8
	v_max_f32_e32 v4, v15, v10
	v_min_f32_e32 v10, v15, v10
	v_max_f32_e32 v205, v7, v241
	v_min_f32_e32 v241, v7, v241
	v_max_f32_e32 v7, v5, v2
	v_min_f32_e32 v2, v5, v2
	v_max_f32_e32 v5, v239, v240
	v_min_f32_e32 v240, v239, v240
	v_max_f32_e32 v239, v242, v3
	v_min_f32_e32 v3, v242, v3
	v_max_f32_e32 v242, v243, v4
	v_min_f32_e32 v4, v243, v4
	v_min_f32_e32 v237, v8, v10
	v_max_f32_e32 v8, v8, v10
	v_max_f32_e32 v206, v7, v241
	v_min_f32_e32 v241, v7, v241
	v_max_f32_e32 v243, v9, v2
	v_min_f32_e32 v2, v9, v2
	v_max_f32_e32 v7, v242, v6
	v_min_f32_e32 v6, v242, v6
	v_min_f32_e32 v236, v8, v4
	v_max_f32_e32 v8, v8, v4
	v_max_f32_e32 v242, v243, v5
	v_min_f32_e32 v5, v243, v5
	v_max_f32_e32 v243, v2, v240
	v_min_f32_e32 v240, v2, v240
	v_max_f32_e32 v2, v239, v7
	v_min_f32_e32 v7, v239, v7
	v_max_f32_e32 v239, v3, v6
	v_min_f32_e32 v6, v3, v6
	v_max_f32_e32 v207, v242, v241
	v_min_f32_e32 v227, v242, v241
	v_max_f32_e32 v228, v5, v243
	v_min_f32_e32 v243, v5, v243
	v_max_f32_e32 v241, v2, v240
	v_min_f32_e32 v240, v2, v240
	v_min_f32_e32 v233, v7, v239
	v_max_f32_e32 v7, v7, v239
	v_max_f32_e32 v234, v8, v6
	v_min_f32_e32 v235, v8, v6
	v_max_f32_e32 v229, v243, v241
	v_min_f32_e32 v230, v243, v241
	v_max_f32_e32 v231, v240, v7
	v_min_f32_e32 v232, v240, v7
	s_waitcnt vmcnt(0)
	v_mfma_f32_32x32x16_bf16 v[2:17], v[244:247], v[46:49], 0
	v_mfma_f32_32x32x16_bf16 v[2:17], v[58:61], v[42:45], v[2:17]
	v_mfma_f32_32x32x16_bf16 v[2:17], v[54:57], v[38:41], v[2:17]
	v_mfma_f32_32x32x16_bf16 v[2:17], v[50:53], v[34:37], v[2:17]
	s_nop 11
	v_and_or_b32 v2, v2, s33, v143
	v_and_or_b32 v3, v3, s33, v144
	v_and_or_b32 v4, v4, s33, v145
	v_and_or_b32 v5, v5, s33, v146
	v_and_or_b32 v6, v6, s33, v147
	v_and_or_b32 v7, v7, s33, v148
	v_and_or_b32 v8, v8, s33, v149
	v_and_or_b32 v9, v9, s33, v150
	v_and_or_b32 v10, v10, s33, v151
	v_and_or_b32 v11, v11, s33, v152
	v_and_or_b32 v12, v12, s33, v153
	v_and_or_b32 v13, v13, s33, v160
	v_and_or_b32 v14, v14, s33, v161
	v_and_or_b32 v15, v15, s33, v162
	v_and_or_b32 v16, v16, s33, v163
	v_and_or_b32 v17, v17, s33, v164
	global_load_dwordx4 v[50:53], v[94:95], off offset:96
	global_load_dwordx4 v[54:57], v[94:95], off offset:64
	global_load_dwordx4 v[58:61], v[94:95], off offset:32
	global_load_dwordx4 v[244:247], v[94:95], off
	v_max_f32_e32 v239, v2, v15
	v_min_f32_e32 v15, v2, v15
	v_max_f32_e32 v2, v3, v14
	v_min_f32_e32 v14, v3, v14
	v_max_f32_e32 v3, v4, v17
	v_min_f32_e32 v17, v4, v17
	v_max_f32_e32 v4, v5, v16
	v_min_f32_e32 v16, v5, v16
	v_max_f32_e32 v5, v6, v10
	v_min_f32_e32 v10, v6, v10
	v_max_f32_e32 v6, v7, v8
	v_min_f32_e32 v8, v7, v8
	v_max_f32_e32 v7, v9, v13
	v_min_f32_e32 v13, v9, v13
	v_max_f32_e32 v9, v11, v12
	v_min_f32_e32 v12, v11, v12
	v_max_f32_e32 v11, v239, v6
	v_min_f32_e32 v6, v239, v6
	v_max_f32_e32 v239, v2, v7
	v_min_f32_e32 v7, v2, v7
	v_max_f32_e32 v2, v3, v9
	v_min_f32_e32 v9, v3, v9
	v_max_f32_e32 v3, v4, v5
	v_min_f32_e32 v5, v4, v5
	v_max_f32_e32 v4, v8, v15
	v_min_f32_e32 v15, v8, v15
	v_max_f32_e32 v8, v10, v16
	v_min_f32_e32 v16, v10, v16
	v_max_f32_e32 v10, v12, v17
	v_min_f32_e32 v17, v12, v17
	v_max_f32_e32 v12, v13, v14
	v_min_f32_e32 v14, v13, v14
	v_max_f32_e32 v13, v11, v239
	v_min_f32_e32 v239, v11, v239
	v_max_f32_e32 v11, v2, v3
	v_min_f32_e32 v3, v2, v3
	v_max_f32_e32 v2, v5, v6
	v_min_f32_e32 v6, v5, v6
	v_max_f32_e32 v5, v4, v8
	v_min_f32_e32 v8, v4, v8
	v_max_f32_e32 v4, v7, v9
	v_min_f32_e32 v9, v7, v9
	v_max_f32_e32 v7, v10, v12
	v_min_f32_e32 v12, v10, v12
	v_max_f32_e32 v10, v14, v15
	v_min_f32_e32 v15, v14, v15
	v_max_f32_e32 v14, v16, v17
	v_min_f32_e32 v17, v16, v17
	v_max_f32_e32 v16, v13, v11
	v_min_f32_e32 v11, v13, v11
	v_max_f32_e32 v13, v239, v3
	v_min_f32_e32 v3, v239, v3
	v_max_f32_e32 v239, v2, v7
	v_min_f32_e32 v7, v2, v7
	v_max_f32_e32 v2, v6, v12
	v_min_f32_e32 v12, v6, v12
	v_max_f32_e32 v6, v5, v4
	v_min_f32_e32 v4, v5, v4
	v_max_f32_e32 v5, v8, v9
	v_min_f32_e32 v9, v8, v9
	v_max_f32_e32 v8, v10, v14
	v_min_f32_e32 v14, v10, v14
	v_max_f32_e32 v10, v15, v17
	v_min_f32_e32 v17, v15, v17
	v_max_f32_e32 v15, v13, v11
	v_min_f32_e32 v11, v13, v11
	v_max_f32_e32 v13, v3, v8
	v_min_f32_e32 v8, v3, v8
	v_max_f32_e32 v3, v239, v6
	v_min_f32_e32 v6, v239, v6
	v_max_f32_e32 v239, v2, v4
	v_min_f32_e32 v4, v2, v4
	v_max_f32_e32 v2, v5, v7
	v_min_f32_e32 v7, v5, v7
	v_max_f32_e32 v5, v9, v12
	v_min_f32_e32 v12, v9, v12
	v_max_f32_e32 v9, v10, v14
	v_min_f32_e32 v14, v10, v14
	v_max_f32_e32 v10, v15, v3
	v_min_f32_e32 v3, v15, v3
	v_max_f32_e32 v15, v11, v6
	v_min_f32_e32 v6, v11, v6
	v_max_f32_e32 v11, v239, v2
	v_min_f32_e32 v2, v239, v2
	v_max_f32_e32 v239, v4, v7
	v_min_f32_e32 v7, v4, v7
	v_max_f32_e32 v4, v5, v9
	v_min_f32_e32 v9, v5, v9
	v_max_f32_e32 v5, v12, v14
	v_min_f32_e32 v14, v12, v14
	v_max_f32_e32 v12, v15, v3
	v_min_f32_e32 v3, v15, v3
	v_max_f32_e32 v15, v13, v6
	v_min_f32_e32 v6, v13, v6
	v_max_f32_e32 v13, v4, v8
	v_min_f32_e32 v8, v4, v8
	v_max_f32_e32 v4, v5, v9
	v_min_f32_e32 v9, v5, v9
	v_max_f32_e32 v5, v15, v11
	v_min_f32_e32 v11, v15, v11
	v_max_f32_e32 v15, v6, v2
	v_min_f32_e32 v2, v6, v2
	v_max_f32_e32 v6, v239, v13
	v_min_f32_e32 v13, v239, v13
	v_max_f32_e32 v239, v7, v8
	v_min_f32_e32 v8, v7, v8
	v_max_f32_e32 v7, v5, v3
	v_min_f32_e32 v3, v5, v3
	v_max_f32_e32 v5, v11, v15
	v_min_f32_e32 v15, v11, v15
	v_max_f32_e32 v11, v6, v2
	v_min_f32_e32 v2, v6, v2
	v_max_f32_e32 v6, v13, v239
	v_min_f32_e32 v239, v13, v239
	v_max_f32_e32 v13, v4, v8
	v_min_f32_e32 v8, v4, v8
	v_max_f32_e32 v4, v15, v11
	v_min_f32_e32 v11, v15, v11
	v_max_f32_e32 v15, v2, v6
	v_min_f32_e32 v6, v2, v6
	v_max_f32_e32 v17, v154, v17
	v_max_f32_e32 v14, v205, v14
	v_max_f32_e32 v9, v206, v9
	v_max_f32_e32 v8, v207, v8
	v_max_f32_e32 v13, v227, v13
	v_max_f32_e32 v239, v228, v239
	v_max_f32_e32 v6, v229, v6
	v_max_f32_e32 v15, v230, v15
	v_max_f32_e32 v11, v231, v11
	v_max_f32_e32 v4, v232, v4
	v_max_f32_e32 v5, v233, v5
	v_max_f32_e32 v3, v234, v3
	v_max_f32_e32 v7, v235, v7
	v_max_f32_e32 v12, v236, v12
	v_max_f32_e32 v10, v237, v10
	v_max_f32_e32 v16, v238, v16
	v_max_f32_e32 v2, v16, v15
	v_min_f32_e32 v15, v16, v15
	v_max_f32_e32 v16, v10, v6
	v_min_f32_e32 v6, v10, v6
	v_max_f32_e32 v10, v12, v239
	v_min_f32_e32 v239, v12, v239
	v_max_f32_e32 v12, v7, v13
	v_min_f32_e32 v13, v7, v13
	v_max_f32_e32 v7, v3, v8
	v_min_f32_e32 v8, v3, v8
	v_max_f32_e32 v3, v5, v9
	v_min_f32_e32 v9, v5, v9
	v_max_f32_e32 v5, v4, v14
	v_min_f32_e32 v14, v4, v14
	v_max_f32_e32 v4, v11, v17
	v_min_f32_e32 v17, v11, v17
	v_max_f32_e32 v11, v2, v7
	v_min_f32_e32 v7, v2, v7
	v_max_f32_e32 v2, v16, v3
	v_min_f32_e32 v3, v16, v3
	v_max_f32_e32 v16, v10, v5
	v_min_f32_e32 v5, v10, v5
	v_max_f32_e32 v10, v12, v4
	v_min_f32_e32 v4, v12, v4
	v_max_f32_e32 v12, v15, v8
	v_min_f32_e32 v8, v15, v8
	v_max_f32_e32 v15, v6, v9
	v_min_f32_e32 v9, v6, v9
	v_max_f32_e32 v6, v239, v14
	v_min_f32_e32 v14, v239, v14
	v_max_f32_e32 v154, v13, v17
	v_min_f32_e32 v17, v13, v17
	v_max_f32_e32 v13, v11, v16
	v_min_f32_e32 v16, v11, v16
	v_max_f32_e32 v11, v2, v10
	v_min_f32_e32 v10, v2, v10
	v_max_f32_e32 v2, v7, v5
	v_min_f32_e32 v5, v7, v5
	v_max_f32_e32 v7, v3, v4
	v_min_f32_e32 v4, v3, v4
	v_max_f32_e32 v3, v12, v6
	v_min_f32_e32 v6, v12, v6
	v_max_f32_e32 v12, v15, v154
	v_min_f32_e32 v154, v15, v154
	v_max_f32_e32 v15, v8, v14
	v_min_f32_e32 v14, v8, v14
	v_max_f32_e32 v8, v9, v17
	v_min_f32_e32 v17, v9, v17
	v_max_f32_e32 v239, v13, v11
	v_min_f32_e32 v240, v13, v11
	v_max_f32_e32 v241, v16, v10
	v_min_f32_e32 v242, v16, v10
	v_max_f32_e32 v243, v2, v7
	v_min_f32_e32 v252, v2, v7
	v_max_f32_e32 v253, v5, v4
	v_min_f32_e32 v4, v5, v4
	v_max_f32_e32 v205, v3, v12
	v_min_f32_e32 v206, v3, v12
	v_max_f32_e32 v207, v6, v154
	v_min_f32_e32 v227, v6, v154
	v_max_f32_e32 v228, v15, v8
	v_min_f32_e32 v229, v15, v8
	v_max_f32_e32 v230, v14, v17
	v_min_f32_e32 v231, v14, v17
	v_mov_b32_e32 v154, v4
	s_waitcnt vmcnt(0)
	v_mfma_f32_32x32x16_bf16 v[2:17], v[244:247], v[46:49], 0
	v_mfma_f32_32x32x16_bf16 v[2:17], v[58:61], v[42:45], v[2:17]
	v_mfma_f32_32x32x16_bf16 v[2:17], v[54:57], v[38:41], v[2:17]
	v_mfma_f32_32x32x16_bf16 v[2:17], v[50:53], v[34:37], v[2:17]
	s_nop 11
	v_and_or_b32 v2, v2, s33, v165
	v_and_or_b32 v3, v3, s33, v166
	v_and_or_b32 v4, v4, s33, v167
	v_and_or_b32 v5, v5, s33, v168
	v_and_or_b32 v6, v6, s33, v169
	v_and_or_b32 v7, v7, s33, v170
	v_and_or_b32 v8, v8, s33, v171
	v_and_or_b32 v9, v9, s33, v172
	v_and_or_b32 v10, v10, s33, v173
	v_and_or_b32 v11, v11, s33, v174
	v_and_or_b32 v12, v12, s33, v175
	v_and_or_b32 v13, v13, s33, v184
	v_and_or_b32 v14, v14, s33, v185
	v_and_or_b32 v15, v15, s33, v186
	v_and_or_b32 v16, v16, s33, v187
	v_and_or_b32 v17, v17, s33, v188
	global_load_dwordx4 v[50:53], v[96:97], off offset:96
	global_load_dwordx4 v[54:57], v[96:97], off offset:64
	global_load_dwordx4 v[58:61], v[96:97], off offset:32
	global_load_dwordx4 v[244:247], v[96:97], off
	v_max_f32_e32 v232, v2, v15
	v_min_f32_e32 v15, v2, v15
	v_max_f32_e32 v2, v3, v14
	v_min_f32_e32 v14, v3, v14
	v_max_f32_e32 v3, v4, v17
	v_min_f32_e32 v17, v4, v17
	v_max_f32_e32 v4, v5, v16
	v_min_f32_e32 v16, v5, v16
	v_max_f32_e32 v5, v6, v10
	v_min_f32_e32 v10, v6, v10
	v_max_f32_e32 v6, v7, v8
	v_min_f32_e32 v8, v7, v8
	v_max_f32_e32 v7, v9, v13
	v_min_f32_e32 v13, v9, v13
	v_max_f32_e32 v9, v11, v12
	v_min_f32_e32 v12, v11, v12
	v_max_f32_e32 v11, v232, v6
	v_min_f32_e32 v6, v232, v6
	v_max_f32_e32 v232, v2, v7
	v_min_f32_e32 v7, v2, v7
	v_max_f32_e32 v2, v3, v9
	v_min_f32_e32 v9, v3, v9
	v_max_f32_e32 v3, v4, v5
	v_min_f32_e32 v5, v4, v5
	v_max_f32_e32 v4, v8, v15
	v_min_f32_e32 v15, v8, v15
	v_max_f32_e32 v8, v10, v16
	v_min_f32_e32 v16, v10, v16
	v_max_f32_e32 v10, v12, v17
	v_min_f32_e32 v17, v12, v17
	v_max_f32_e32 v12, v13, v14
	v_min_f32_e32 v14, v13, v14
	v_max_f32_e32 v13, v11, v232
	v_min_f32_e32 v232, v11, v232
	v_max_f32_e32 v11, v2, v3
	v_min_f32_e32 v3, v2, v3
	v_max_f32_e32 v2, v5, v6
	v_min_f32_e32 v6, v5, v6
	v_max_f32_e32 v5, v4, v8
	v_min_f32_e32 v8, v4, v8
	v_max_f32_e32 v4, v7, v9
	v_min_f32_e32 v9, v7, v9
	v_max_f32_e32 v7, v10, v12
	v_min_f32_e32 v12, v10, v12
	v_max_f32_e32 v10, v14, v15
	v_min_f32_e32 v15, v14, v15
	v_max_f32_e32 v14, v16, v17
	v_min_f32_e32 v17, v16, v17
	v_max_f32_e32 v16, v13, v11
	v_min_f32_e32 v11, v13, v11
	v_max_f32_e32 v13, v232, v3
	v_min_f32_e32 v3, v232, v3
	v_max_f32_e32 v232, v2, v7
	v_min_f32_e32 v7, v2, v7
	v_max_f32_e32 v2, v6, v12
	v_min_f32_e32 v12, v6, v12
	v_max_f32_e32 v6, v5, v4
	v_min_f32_e32 v4, v5, v4
	v_max_f32_e32 v5, v8, v9
	v_min_f32_e32 v9, v8, v9
	v_max_f32_e32 v8, v10, v14
	v_min_f32_e32 v14, v10, v14
	v_max_f32_e32 v10, v15, v17
	v_min_f32_e32 v17, v15, v17
	v_max_f32_e32 v15, v13, v11
	v_min_f32_e32 v11, v13, v11
	v_max_f32_e32 v13, v3, v8
	v_min_f32_e32 v8, v3, v8
	v_max_f32_e32 v3, v232, v6
	v_min_f32_e32 v6, v232, v6
	v_max_f32_e32 v232, v2, v4
	v_min_f32_e32 v4, v2, v4
	v_max_f32_e32 v2, v5, v7
	v_min_f32_e32 v7, v5, v7
	v_max_f32_e32 v5, v9, v12
	v_min_f32_e32 v12, v9, v12
	v_max_f32_e32 v9, v10, v14
	v_min_f32_e32 v14, v10, v14
	v_max_f32_e32 v10, v15, v3
	v_min_f32_e32 v3, v15, v3
	v_max_f32_e32 v15, v11, v6
	v_min_f32_e32 v6, v11, v6
	v_max_f32_e32 v11, v232, v2
	v_min_f32_e32 v2, v232, v2
	v_max_f32_e32 v232, v4, v7
	v_min_f32_e32 v7, v4, v7
	v_max_f32_e32 v4, v5, v9
	v_min_f32_e32 v9, v5, v9
	v_max_f32_e32 v5, v12, v14
	v_min_f32_e32 v14, v12, v14
	v_max_f32_e32 v12, v15, v3
	v_min_f32_e32 v3, v15, v3
	v_max_f32_e32 v15, v13, v6
	v_min_f32_e32 v6, v13, v6
	v_max_f32_e32 v13, v4, v8
	v_min_f32_e32 v8, v4, v8
	v_max_f32_e32 v4, v5, v9
	v_min_f32_e32 v9, v5, v9
	v_max_f32_e32 v5, v15, v11
	v_min_f32_e32 v11, v15, v11
	v_max_f32_e32 v15, v6, v2
	v_min_f32_e32 v2, v6, v2
	v_max_f32_e32 v6, v232, v13
	v_min_f32_e32 v13, v232, v13
	v_max_f32_e32 v232, v7, v8
	v_min_f32_e32 v8, v7, v8
	v_max_f32_e32 v7, v5, v3
	v_min_f32_e32 v3, v5, v3
	v_max_f32_e32 v5, v11, v15
	v_min_f32_e32 v15, v11, v15
	v_max_f32_e32 v11, v6, v2
	v_min_f32_e32 v2, v6, v2
	v_max_f32_e32 v6, v13, v232
	v_min_f32_e32 v232, v13, v232
	v_max_f32_e32 v13, v4, v8
	v_min_f32_e32 v8, v4, v8
	v_max_f32_e32 v4, v15, v11
	v_min_f32_e32 v11, v15, v11
	v_max_f32_e32 v15, v2, v6
	v_min_f32_e32 v6, v2, v6
	v_max_f32_e32 v17, v239, v17
	v_max_f32_e32 v14, v240, v14
	v_max_f32_e32 v9, v241, v9
	v_max_f32_e32 v8, v242, v8
	v_max_f32_e32 v13, v243, v13
	v_max_f32_e32 v232, v252, v232
	v_max_f32_e32 v6, v253, v6
	v_max_f32_e32 v15, v154, v15
	v_max_f32_e32 v11, v205, v11
	v_max_f32_e32 v4, v206, v4
	v_max_f32_e32 v5, v207, v5
	v_max_f32_e32 v3, v227, v3
	v_max_f32_e32 v7, v228, v7
	v_max_f32_e32 v12, v229, v12
	v_max_f32_e32 v10, v230, v10
	v_max_f32_e32 v16, v231, v16
	v_max_f32_e32 v2, v16, v15
	v_min_f32_e32 v15, v16, v15
	v_max_f32_e32 v16, v10, v6
	v_min_f32_e32 v6, v10, v6
	v_max_f32_e32 v10, v12, v232
	v_min_f32_e32 v232, v12, v232
	v_max_f32_e32 v12, v7, v13
	v_min_f32_e32 v13, v7, v13
	v_max_f32_e32 v7, v3, v8
	v_min_f32_e32 v8, v3, v8
	v_max_f32_e32 v3, v5, v9
	v_min_f32_e32 v9, v5, v9
	v_max_f32_e32 v5, v4, v14
	v_min_f32_e32 v14, v4, v14
	v_max_f32_e32 v4, v11, v17
	v_min_f32_e32 v17, v11, v17
	v_max_f32_e32 v11, v2, v7
	v_min_f32_e32 v7, v2, v7
	v_max_f32_e32 v2, v16, v3
	v_min_f32_e32 v3, v16, v3
	v_max_f32_e32 v16, v10, v5
	v_min_f32_e32 v5, v10, v5
	v_max_f32_e32 v10, v12, v4
	v_min_f32_e32 v4, v12, v4
	v_max_f32_e32 v12, v15, v8
	v_min_f32_e32 v8, v15, v8
	v_max_f32_e32 v15, v6, v9
	v_min_f32_e32 v9, v6, v9
	v_max_f32_e32 v6, v232, v14
	v_min_f32_e32 v14, v232, v14
	v_max_f32_e32 v239, v13, v17
	v_min_f32_e32 v17, v13, v17
	v_max_f32_e32 v13, v11, v16
	v_min_f32_e32 v16, v11, v16
	v_max_f32_e32 v11, v2, v10
	v_min_f32_e32 v10, v2, v10
	v_max_f32_e32 v2, v7, v5
	v_min_f32_e32 v5, v7, v5
	v_max_f32_e32 v7, v3, v4
	v_min_f32_e32 v4, v3, v4
	v_max_f32_e32 v3, v12, v6
	v_min_f32_e32 v6, v12, v6
	v_max_f32_e32 v12, v15, v239
	v_min_f32_e32 v239, v15, v239
	v_max_f32_e32 v15, v8, v14
	v_min_f32_e32 v14, v8, v14
	v_max_f32_e32 v8, v9, v17
	v_min_f32_e32 v17, v9, v17
	v_max_f32_e32 v232, v13, v11
	v_min_f32_e32 v233, v13, v11
	v_max_f32_e32 v234, v16, v10
	v_min_f32_e32 v235, v16, v10
	v_max_f32_e32 v236, v2, v7
	v_min_f32_e32 v237, v2, v7
	v_max_f32_e32 v238, v5, v4
	v_min_f32_e32 v154, v5, v4
	v_max_f32_e32 v205, v3, v12
	v_min_f32_e32 v206, v3, v12
	v_max_f32_e32 v207, v6, v239
	v_min_f32_e32 v227, v6, v239
	v_max_f32_e32 v228, v15, v8
	v_min_f32_e32 v229, v15, v8
	v_max_f32_e32 v230, v14, v17
	v_min_f32_e32 v231, v14, v17
	s_waitcnt vmcnt(0)
	v_mfma_f32_32x32x16_bf16 v[2:17], v[244:247], v[46:49], 0
	v_mfma_f32_32x32x16_bf16 v[2:17], v[58:61], v[42:45], v[2:17]
	v_mfma_f32_32x32x16_bf16 v[2:17], v[54:57], v[38:41], v[2:17]
	v_mfma_f32_32x32x16_bf16 v[2:17], v[50:53], v[34:37], v[2:17]
	s_nop 11
	v_and_or_b32 v2, v2, s33, v189
	v_and_or_b32 v3, v3, s33, v190
	v_and_or_b32 v4, v4, s33, v191
	v_and_or_b32 v5, v5, s33, v192
	v_and_or_b32 v6, v6, s33, v193
	v_and_or_b32 v7, v7, s33, v194
	v_and_or_b32 v8, v8, s33, v195
	v_and_or_b32 v9, v9, s33, v196
	v_and_or_b32 v10, v10, s33, v197
	v_and_or_b32 v11, v11, s33, v198
	v_and_or_b32 v12, v12, s33, v199
	v_and_or_b32 v13, v13, s33, v200
	v_and_or_b32 v14, v14, s33, v201
	v_and_or_b32 v15, v15, s33, v202
	v_and_or_b32 v16, v16, s33, v203
	v_and_or_b32 v17, v17, s33, v204
	v_max_f32_e32 v35, v2, v15
	v_min_f32_e32 v15, v2, v15
	v_max_f32_e32 v36, v3, v14
	v_min_f32_e32 v14, v3, v14
	v_max_f32_e32 v37, v4, v17
	v_min_f32_e32 v17, v4, v17
	v_max_f32_e32 v38, v5, v16
	v_min_f32_e32 v16, v5, v16
	v_max_f32_e32 v39, v6, v10
	v_min_f32_e32 v10, v6, v10
	v_max_f32_e32 v40, v7, v8
	v_min_f32_e32 v8, v7, v8
	v_max_f32_e32 v41, v9, v13
	v_min_f32_e32 v13, v9, v13
	v_max_f32_e32 v42, v11, v12
	v_min_f32_e32 v12, v11, v12
	v_max_f32_e32 v43, v35, v40
	v_min_f32_e32 v40, v35, v40
	v_max_f32_e32 v35, v36, v41
	v_min_f32_e32 v41, v36, v41
	v_max_f32_e32 v36, v37, v42
	v_min_f32_e32 v42, v37, v42
	v_max_f32_e32 v37, v38, v39
	v_min_f32_e32 v39, v38, v39
	v_max_f32_e32 v38, v8, v15
	v_min_f32_e32 v15, v8, v15
	v_max_f32_e32 v44, v10, v16
	v_min_f32_e32 v16, v10, v16
	v_max_f32_e32 v45, v12, v17
	v_min_f32_e32 v17, v12, v17
	v_max_f32_e32 v46, v13, v14
	v_min_f32_e32 v14, v13, v14
	v_max_f32_e32 v47, v43, v35
	v_min_f32_e32 v35, v43, v35
	v_max_f32_e32 v43, v36, v37
	v_min_f32_e32 v37, v36, v37
	v_max_f32_e32 v36, v39, v40
	v_min_f32_e32 v40, v39, v40
	v_max_f32_e32 v39, v38, v44
	v_min_f32_e32 v44, v38, v44
	v_max_f32_e32 v38, v41, v42
	v_min_f32_e32 v42, v41, v42
	v_max_f32_e32 v41, v45, v46
	v_min_f32_e32 v46, v45, v46
	v_max_f32_e32 v45, v14, v15
	v_min_f32_e32 v15, v14, v15
	v_max_f32_e32 v48, v16, v17
	v_min_f32_e32 v17, v16, v17
	v_max_f32_e32 v2, v47, v43
	v_min_f32_e32 v43, v47, v43
	v_max_f32_e32 v47, v35, v37
	v_min_f32_e32 v37, v35, v37
	v_max_f32_e32 v35, v36, v41
	v_min_f32_e32 v41, v36, v41
	v_max_f32_e32 v36, v40, v46
	v_min_f32_e32 v46, v40, v46
	v_max_f32_e32 v40, v39, v38
	v_min_f32_e32 v38, v39, v38
	v_max_f32_e32 v39, v44, v42
	v_min_f32_e32 v42, v44, v42
	v_max_f32_e32 v44, v45, v48
	v_min_f32_e32 v48, v45, v48
	v_max_f32_e32 v45, v15, v17
	v_min_f32_e32 v17, v15, v17
	v_max_f32_e32 v3, v47, v43
	v_min_f32_e32 v43, v47, v43
	v_max_f32_e32 v47, v37, v44
	v_min_f32_e32 v44, v37, v44
	v_max_f32_e32 v37, v35, v40
	v_min_f32_e32 v40, v35, v40
	v_max_f32_e32 v35, v36, v38
	v_min_f32_e32 v38, v36, v38
	v_max_f32_e32 v36, v39, v41
	v_min_f32_e32 v41, v39, v41
	v_max_f32_e32 v39, v42, v46
	v_min_f32_e32 v46, v42, v46
	v_max_f32_e32 v42, v45, v48
	v_min_f32_e32 v48, v45, v48
	v_max_f32_e32 v45, v3, v37
	v_min_f32_e32 v37, v3, v37
	v_max_f32_e32 v3, v43, v40
	v_min_f32_e32 v40, v43, v40
	v_max_f32_e32 v43, v35, v36
	v_min_f32_e32 v36, v35, v36
	v_max_f32_e32 v35, v38, v41
	v_min_f32_e32 v41, v38, v41
	v_max_f32_e32 v38, v39, v42
	v_min_f32_e32 v42, v39, v42
	v_max_f32_e32 v39, v46, v48
	v_min_f32_e32 v48, v46, v48
	v_max_f32_e32 v46, v3, v37
	v_min_f32_e32 v37, v3, v37
	v_max_f32_e32 v3, v47, v40
	v_min_f32_e32 v40, v47, v40
	v_max_f32_e32 v47, v38, v44
	v_min_f32_e32 v44, v38, v44
	v_max_f32_e32 v38, v39, v42
	v_min_f32_e32 v42, v39, v42
	v_max_f32_e32 v39, v3, v43
	v_min_f32_e32 v43, v3, v43
	v_max_f32_e32 v3, v40, v36
	v_min_f32_e32 v36, v40, v36
	v_max_f32_e32 v40, v35, v47
	v_min_f32_e32 v47, v35, v47
	v_max_f32_e32 v35, v41, v44
	v_min_f32_e32 v44, v41, v44
	v_max_f32_e32 v41, v39, v37
	v_min_f32_e32 v37, v39, v37
	v_max_f32_e32 v39, v43, v3
	v_min_f32_e32 v3, v43, v3
	v_max_f32_e32 v43, v40, v36
	v_min_f32_e32 v36, v40, v36
	v_max_f32_e32 v40, v47, v35
	v_min_f32_e32 v35, v47, v35
	v_max_f32_e32 v47, v38, v44
	v_min_f32_e32 v44, v38, v44
	v_max_f32_e32 v38, v3, v43
	v_min_f32_e32 v43, v3, v43
	v_max_f32_e32 v3, v36, v40
	v_min_f32_e32 v40, v36, v40
	v_max_f32_e32 v17, v232, v17
	v_max_f32_e32 v48, v233, v48
	v_max_f32_e32 v42, v234, v42
	v_max_f32_e32 v44, v235, v44
	v_max_f32_e32 v47, v236, v47
	v_max_f32_e32 v35, v237, v35
	v_max_f32_e32 v40, v238, v40
	v_max_f32_e32 v3, v154, v3
	v_max_f32_e32 v43, v205, v43
	v_max_f32_e32 v38, v206, v38
	v_max_f32_e32 v39, v207, v39
	v_max_f32_e32 v37, v227, v37
	v_max_f32_e32 v41, v228, v41
	v_max_f32_e32 v46, v229, v46
	v_max_f32_e32 v45, v230, v45
	v_max_f32_e32 v2, v231, v2
	v_max_f32_e32 v36, v2, v3
	v_min_f32_e32 v3, v2, v3
	v_max_f32_e32 v2, v45, v40
	v_min_f32_e32 v40, v45, v40
	v_max_f32_e32 v45, v46, v35
	v_min_f32_e32 v35, v46, v35
	v_max_f32_e32 v46, v41, v47
	v_min_f32_e32 v47, v41, v47
	v_max_f32_e32 v41, v37, v44
	v_min_f32_e32 v44, v37, v44
	v_max_f32_e32 v37, v39, v42
	v_min_f32_e32 v42, v39, v42
	v_max_f32_e32 v39, v38, v48
	v_min_f32_e32 v48, v38, v48
	v_max_f32_e32 v38, v43, v17
	v_min_f32_e32 v17, v43, v17
	v_max_f32_e32 v43, v36, v41
	v_min_f32_e32 v41, v36, v41
	v_max_f32_e32 v36, v2, v37
	v_min_f32_e32 v37, v2, v37
	v_max_f32_e32 v2, v45, v39
	v_min_f32_e32 v39, v45, v39
	v_max_f32_e32 v45, v46, v38
	v_min_f32_e32 v38, v46, v38
	v_max_f32_e32 v46, v3, v44
	v_min_f32_e32 v44, v3, v44
	v_max_f32_e32 v3, v40, v42
	v_min_f32_e32 v42, v40, v42
	v_max_f32_e32 v40, v35, v48
	v_min_f32_e32 v48, v35, v48
	v_max_f32_e32 v35, v47, v17
	v_min_f32_e32 v17, v47, v17
	v_max_f32_e32 v47, v43, v2
	v_min_f32_e32 v2, v43, v2
	v_max_f32_e32 v43, v36, v45
	v_min_f32_e32 v45, v36, v45
	v_max_f32_e32 v36, v41, v39
	v_min_f32_e32 v39, v41, v39
	v_max_f32_e32 v41, v37, v38
	v_min_f32_e32 v38, v37, v38
	v_max_f32_e32 v37, v46, v40
	v_min_f32_e32 v40, v46, v40
	v_max_f32_e32 v46, v3, v35
	v_min_f32_e32 v35, v3, v35
	v_max_f32_e32 v3, v44, v48
	v_min_f32_e32 v48, v44, v48
	v_max_f32_e32 v44, v42, v17
	v_min_f32_e32 v17, v42, v17
	v_max_f32_e32 v15, v47, v43
	v_min_f32_e32 v43, v47, v43
	v_max_f32_e32 v12, v2, v45
	v_min_f32_e32 v5, v2, v45
	v_max_f32_e32 v9, v36, v41
	v_min_f32_e32 v41, v36, v41
	v_max_f32_e32 v34, v39, v38
	v_min_f32_e32 v4, v39, v38
	v_max_f32_e32 v11, v37, v46
	v_min_f32_e32 v13, v37, v46
	v_max_f32_e32 v16, v40, v35
	v_min_f32_e32 v7, v40, v35
	v_max_f32_e32 v14, v3, v44
	v_min_f32_e32 v8, v3, v44
	v_max_f32_e32 v10, v48, v17
	v_min_f32_e32 v2, v48, v17
	v_mov_b32_e32 v3, v43
	v_mov_b32_e32 v17, v41
	ds_bpermute_b32 v6, v121, v15
	ds_bpermute_b32 v35, v121, v3
	ds_bpermute_b32 v36, v121, v12
	ds_bpermute_b32 v37, v121, v5
	ds_bpermute_b32 v38, v121, v9
	ds_bpermute_b32 v39, v121, v17
	ds_bpermute_b32 v40, v121, v34
	ds_bpermute_b32 v41, v121, v4
	ds_bpermute_b32 v42, v121, v11
	ds_bpermute_b32 v43, v121, v13
	ds_bpermute_b32 v44, v121, v16
	ds_bpermute_b32 v45, v121, v7
	ds_bpermute_b32 v46, v121, v14
	ds_bpermute_b32 v47, v121, v8
	ds_bpermute_b32 v48, v121, v10
	ds_bpermute_b32 v49, v121, v2
	s_waitcnt lgkmcnt(4)
	s_waitcnt lgkmcnt(3)
	s_waitcnt lgkmcnt(2)
	s_waitcnt lgkmcnt(1)
	s_waitcnt lgkmcnt(0)
	v_max_f32_e32 v15, v15, v49
	v_max_f32_e32 v3, v3, v48
	v_max_f32_e32 v12, v12, v47
	v_max_f32_e32 v5, v5, v46
	v_max_f32_e32 v9, v9, v45
	v_max_f32_e32 v17, v17, v44
	v_max_f32_e32 v34, v34, v43
	v_max_f32_e32 v4, v4, v42
	v_max_f32_e32 v11, v11, v41
	v_max_f32_e32 v13, v13, v40
	v_max_f32_e32 v16, v16, v39
	v_max_f32_e32 v7, v7, v38
	v_max_f32_e32 v14, v14, v37
	v_max_f32_e32 v8, v8, v36
	v_max_f32_e32 v10, v10, v35
	v_max_f32_e32 v2, v2, v6
	v_max_f32_e32 v6, v15, v11
	v_min_f32_e32 v11, v15, v11
	v_max_f32_e32 v15, v3, v13
	v_min_f32_e32 v3, v3, v13
	v_max_f32_e32 v13, v12, v16
	v_min_f32_e32 v12, v12, v16
	v_max_f32_e32 v16, v5, v7
	v_min_f32_e32 v5, v5, v7
	v_max_f32_e32 v7, v9, v14
	v_min_f32_e32 v9, v9, v14
	v_max_f32_e32 v14, v17, v8
	v_min_f32_e32 v8, v17, v8
	v_max_f32_e32 v17, v34, v10
	v_min_f32_e32 v10, v34, v10
	v_max_f32_e32 v34, v4, v2
	v_min_f32_e32 v2, v4, v2
	v_max_f32_e32 v4, v6, v7
	v_min_f32_e32 v6, v6, v7
	v_max_f32_e32 v7, v15, v14
	v_min_f32_e32 v14, v15, v14
	v_max_f32_e32 v15, v13, v17
	v_min_f32_e32 v13, v13, v17
	v_max_f32_e32 v17, v16, v34
	v_min_f32_e32 v16, v16, v34
	v_max_f32_e32 v34, v11, v9
	v_min_f32_e32 v9, v11, v9
	v_max_f32_e32 v11, v3, v8
	v_min_f32_e32 v3, v3, v8
	v_max_f32_e32 v8, v12, v10
	v_min_f32_e32 v10, v12, v10
	v_max_f32_e32 v12, v5, v2
	v_max_f32_e32 v36, v34, v8
	v_min_f32_e32 v8, v34, v8
	v_max_f32_e32 v34, v11, v12
	v_min_f32_e32 v37, v11, v12
	v_max_f32_e32 v38, v9, v10
	v_min_f32_e32 v9, v9, v10
	v_max_f32_e32 v10, v36, v34
	v_min_f32_e32 v11, v36, v34
	v_mov_b32_e32 v34, v119
	v_min_f32_e32 v2, v5, v2
	v_max_f32_e32 v5, v4, v15
	v_min_f32_e32 v15, v4, v15
	v_max_f32_e32 v4, v7, v17
	v_min_f32_e32 v7, v7, v17
	v_max_f32_e32 v17, v6, v13
	v_min_f32_e32 v6, v6, v13
	v_max_f32_e32 v13, v14, v16
	v_min_f32_e32 v35, v14, v16
	v_max_f32_e32 v39, v3, v2
	v_min_f32_e32 v40, v3, v2
	v_and_b32_e32 v34, 31, v34
	v_max_f32_e32 v2, v5, v4
	v_min_f32_e32 v3, v5, v4
	v_max_f32_e32 v4, v15, v7
	v_min_f32_e32 v5, v15, v7
	v_max_f32_e32 v14, v17, v13
	v_min_f32_e32 v15, v17, v13
	v_max_f32_e32 v16, v6, v35
	v_min_f32_e32 v17, v6, v35
	v_max_f32_e32 v12, v8, v37
	v_min_f32_e32 v13, v8, v37
	v_max_f32_e32 v6, v38, v39
	v_min_f32_e32 v7, v38, v39
	v_max_f32_e32 v8, v9, v40
	v_min_f32_e32 v9, v9, v40
	v_lshl_add_u32 v36, v34, 7, s43
	s_lshl_b32 s10, s44, 10
	v_add_u32_e32 v36, s10, v36
	s_and_saveexec_b64 s[40:41], s[12:13]
	s_cbranch_execz .LBB0_24
	ds_write_b128 v36, v[30:33]
	ds_write_b128 v36, v[2:5] offset:64
	ds_write_b128 v36, v[26:29] offset:16
	ds_write_b128 v36, v[14:17] offset:80
	ds_write_b128 v36, v[22:25] offset:32
	ds_write_b128 v36, v[10:13] offset:96
	ds_write_b128 v36, v[18:21] offset:48
	ds_write_b128 v36, v[6:9] offset:112
